# G2 store-pass epilogue: removed 16 serialized wait+dead-copy groups so the gate loads of a group fly together
# speedup vs baseline: 1.0056x; 1.0056x over previous
.LBB0_632:
	s_add_i32 s51, s16, 2
	s_add_u32 s4, s2, 0x100
	s_addc_u32 s5, s3, 0
	s_add_i32 s52, 0, 0x10000
	v_add_u32_e32 v144, s52, v196
	ds_read_b128 v[132:135], v144
	ds_read_b128 v[136:139], v144 offset:1024
	ds_read_b128 v[140:143], v144 offset:2048
	ds_read_b128 v[144:147], v144 offset:3072
	s_cmp_eq_u32 s48, s16
	s_cselect_b32 s16, s0, s4
	s_cselect_b32 s17, s1, s5
	s_cselect_b32 s21, s9, s50
	s_cselect_b32 s20, s8, s49
	v_lshl_add_u64 v[168:169], s[2:3], 0, v[176:177]
	s_add_i32 m0, s23, 0xc000
	ds_read_b128 v[148:151], v198
	ds_read_b128 v[152:155], v198 offset:1024
	ds_read_b128 v[156:159], v198 offset:2048
	ds_read_b128 v[160:163], v198 offset:3072
	ds_read_b128 v[180:183], v198 offset:4096
	ds_read_b128 v[184:187], v198 offset:5120
	ds_read_b128 v[188:191], v198 offset:6144
	ds_read_b128 v[192:195], v198 offset:7168
	global_load_lds_dwordx4 v[168:169], off
	v_lshl_add_u64 v[168:169], s[2:3], 0, v[178:179]
	s_add_i32 m0, s23, 0xe000
	s_nop 0
	global_load_lds_dwordx4 v[168:169], off
	s_waitcnt lgkmcnt(8)
	s_barrier
	s_waitcnt lgkmcnt(0)
	s_waitcnt lgkmcnt(0)
	v_mfma_f32_16x16x32_bf16 v[128:131], v[132:135], v[148:151], v[128:131]
	v_mfma_f32_16x16x32_bf16 v[124:127], v[140:143], v[148:151], v[124:127]
	v_mfma_f32_16x16x32_bf16 v[120:123], v[132:135], v[156:159], v[120:123]
	v_mfma_f32_16x16x32_bf16 v[116:119], v[140:143], v[156:159], v[116:119]
	v_mfma_f32_16x16x32_bf16 v[112:115], v[132:135], v[180:183], v[112:115]
	v_mfma_f32_16x16x32_bf16 v[108:111], v[140:143], v[180:183], v[108:111]
	v_mfma_f32_16x16x32_bf16 v[104:107], v[132:135], v[188:191], v[104:107]
	v_mfma_f32_16x16x32_bf16 v[100:103], v[140:143], v[188:191], v[100:103]
	v_mfma_f32_16x16x32_bf16 v[128:131], v[136:139], v[152:155], v[128:131]
	v_mfma_f32_16x16x32_bf16 v[124:127], v[144:147], v[152:155], v[124:127]
	v_mfma_f32_16x16x32_bf16 v[120:123], v[136:139], v[160:163], v[120:123]
	v_mfma_f32_16x16x32_bf16 v[116:119], v[144:147], v[160:163], v[116:119]
	v_mfma_f32_16x16x32_bf16 v[112:115], v[136:139], v[184:187], v[112:115]
	v_mfma_f32_16x16x32_bf16 v[108:111], v[144:147], v[184:187], v[108:111]
	v_mfma_f32_16x16x32_bf16 v[104:107], v[136:139], v[192:195], v[104:107]
	v_mfma_f32_16x16x32_bf16 v[100:103], v[144:147], v[192:195], v[100:103]
	s_barrier
	s_add_i32 s53, 0, 0x14000
	v_add_u32_e32 v168, s53, v196
	s_add_i32 s2, s52, s22
	ds_read_b128 v[200:203], v168
	ds_read_b128 v[204:207], v168 offset:1024
	ds_read_b128 v[208:211], v168 offset:2048
	ds_read_b128 v[220:223], v168 offset:3072
	v_lshl_add_u64 v[168:169], s[20:21], 0, v[2:3]
	s_mov_b32 m0, s2
	v_lshl_add_u64 v[214:215], s[20:21], 0, v[174:175]
	global_load_lds_dwordx4 v[168:169], off
	s_add_i32 m0, s2, 0x2000
	s_nop 0
	global_load_lds_dwordx4 v[214:215], off
	s_barrier
	s_waitcnt lgkmcnt(0)
	s_waitcnt lgkmcnt(0)
	v_mfma_f32_16x16x32_bf16 v[96:99], v[200:203], v[148:151], v[96:99]
	v_mfma_f32_16x16x32_bf16 v[92:95], v[208:211], v[148:151], v[92:95]
	v_mfma_f32_16x16x32_bf16 v[88:91], v[200:203], v[156:159], v[88:91]
	v_mfma_f32_16x16x32_bf16 v[84:87], v[208:211], v[156:159], v[84:87]
	v_mfma_f32_16x16x32_bf16 v[80:83], v[200:203], v[180:183], v[80:83]
	v_mfma_f32_16x16x32_bf16 v[76:79], v[208:211], v[180:183], v[76:79]
	v_mfma_f32_16x16x32_bf16 v[72:75], v[200:203], v[188:191], v[72:75]
	v_mfma_f32_16x16x32_bf16 v[68:71], v[208:211], v[188:191], v[68:71]
	v_mfma_f32_16x16x32_bf16 v[96:99], v[204:207], v[152:155], v[96:99]
	v_mfma_f32_16x16x32_bf16 v[92:95], v[220:223], v[152:155], v[92:95]
	v_mfma_f32_16x16x32_bf16 v[88:91], v[204:207], v[160:163], v[88:91]
	v_mfma_f32_16x16x32_bf16 v[84:87], v[220:223], v[160:163], v[84:87]
	v_mfma_f32_16x16x32_bf16 v[80:83], v[204:207], v[184:187], v[80:83]
	v_mfma_f32_16x16x32_bf16 v[76:79], v[220:223], v[184:187], v[76:79]
	v_mfma_f32_16x16x32_bf16 v[72:75], v[204:207], v[192:195], v[72:75]
	v_mfma_f32_16x16x32_bf16 v[68:71], v[220:223], v[192:195], v[68:71]
	s_mov_b32 m0, s23
	v_lshl_add_u64 v[224:225], s[16:17], 0, v[0:1]
	s_barrier
	ds_read_b128 v[148:151], v198 offset:16384
	ds_read_b128 v[152:155], v198 offset:17408
	ds_read_b128 v[156:159], v198 offset:18432
	ds_read_b128 v[160:163], v198 offset:19456
	ds_read_b128 v[180:183], v198 offset:20480
	ds_read_b128 v[184:187], v198 offset:21504
	ds_read_b128 v[188:191], v198 offset:22528
	ds_read_b128 v[192:195], v198 offset:23552
	global_load_lds_dwordx4 v[224:225], off
	v_lshl_add_u64 v[234:235], s[16:17], 0, v[172:173]
	s_mov_b32 m0, s26
	s_nop 0
	global_load_lds_dwordx4 v[234:235], off
	s_barrier
	s_waitcnt lgkmcnt(0)
	s_waitcnt lgkmcnt(0)
	v_mfma_f32_16x16x32_bf16 v[64:67], v[132:135], v[148:151], v[64:67]
	v_mfma_f32_16x16x32_bf16 v[60:63], v[140:143], v[148:151], v[60:63]
	v_mfma_f32_16x16x32_bf16 v[56:59], v[132:135], v[156:159], v[56:59]
	v_mfma_f32_16x16x32_bf16 v[52:55], v[140:143], v[156:159], v[52:55]
	v_mfma_f32_16x16x32_bf16 v[48:51], v[132:135], v[180:183], v[48:51]
	v_mfma_f32_16x16x32_bf16 v[44:47], v[140:143], v[180:183], v[44:47]
	v_mfma_f32_16x16x32_bf16 v[40:43], v[132:135], v[188:191], v[40:43]
	v_mfma_f32_16x16x32_bf16 v[36:39], v[140:143], v[188:191], v[36:39]
	v_mfma_f32_16x16x32_bf16 v[64:67], v[136:139], v[152:155], v[64:67]
	v_mfma_f32_16x16x32_bf16 v[60:63], v[144:147], v[152:155], v[60:63]
	v_mfma_f32_16x16x32_bf16 v[56:59], v[136:139], v[160:163], v[56:59]
	v_mfma_f32_16x16x32_bf16 v[52:55], v[144:147], v[160:163], v[52:55]
	v_mfma_f32_16x16x32_bf16 v[48:51], v[136:139], v[184:187], v[48:51]
	v_mfma_f32_16x16x32_bf16 v[44:47], v[144:147], v[184:187], v[44:47]
	v_mfma_f32_16x16x32_bf16 v[40:43], v[136:139], v[192:195], v[40:43]
	v_mfma_f32_16x16x32_bf16 v[36:39], v[144:147], v[192:195], v[36:39]
	s_barrier
	s_add_u32 s2, s20, 0x60000
	s_addc_u32 s3, s21, 0
	s_add_i32 s52, s53, s22
	v_lshl_add_u64 v[132:133], s[2:3], 0, v[2:3]
	s_mov_b32 m0, s52
	s_nop 0
	global_load_lds_dwordx4 v[132:133], off
	v_lshl_add_u64 v[132:133], s[2:3], 0, v[174:175]
	s_add_i32 m0, s52, 0x2000
	s_nop 0
	global_load_lds_dwordx4 v[132:133], off
	s_waitcnt vmcnt(6)
	s_barrier
	v_mfma_f32_16x16x32_bf16 v[32:35], v[200:203], v[148:151], v[32:35]
	v_mfma_f32_16x16x32_bf16 v[28:31], v[208:211], v[148:151], v[28:31]
	v_mfma_f32_16x16x32_bf16 v[24:27], v[200:203], v[156:159], v[24:27]
	v_mfma_f32_16x16x32_bf16 v[20:23], v[208:211], v[156:159], v[20:23]
	v_mfma_f32_16x16x32_bf16 v[16:19], v[200:203], v[180:183], v[16:19]
	v_mfma_f32_16x16x32_bf16 v[12:15], v[208:211], v[180:183], v[12:15]
	v_mfma_f32_16x16x32_bf16 v[8:11], v[200:203], v[188:191], v[8:11]
	v_mfma_f32_16x16x32_bf16 v[4:7], v[208:211], v[188:191], v[4:7]
	v_mfma_f32_16x16x32_bf16 v[32:35], v[204:207], v[152:155], v[32:35]
	v_mfma_f32_16x16x32_bf16 v[28:31], v[220:223], v[152:155], v[28:31]
	v_mfma_f32_16x16x32_bf16 v[24:27], v[204:207], v[160:163], v[24:27]
	v_mfma_f32_16x16x32_bf16 v[20:23], v[220:223], v[160:163], v[20:23]
	v_mfma_f32_16x16x32_bf16 v[16:19], v[204:207], v[184:187], v[16:19]
	v_mfma_f32_16x16x32_bf16 v[12:15], v[220:223], v[184:187], v[12:15]
	v_mfma_f32_16x16x32_bf16 v[8:11], v[204:207], v[192:195], v[8:11]
	v_mfma_f32_16x16x32_bf16 v[4:7], v[220:223], v[192:195], v[4:7]
	s_add_i32 s52, 0, 0x18000
	v_add_u32_e32 v144, s52, v196
	s_barrier
	ds_read_b128 v[132:135], v144
	ds_read_b128 v[136:139], v144 offset:1024
	ds_read_b128 v[140:143], v144 offset:2048
	ds_read_b128 v[144:147], v144 offset:3072
	s_add_u32 s2, s16, 0x60000
	s_addc_u32 s3, s17, 0
	s_mov_b32 m0, s27
	v_lshl_add_u64 v[200:201], s[2:3], 0, v[0:1]
	ds_read_b128 v[148:151], v198 offset:32768
	ds_read_b128 v[152:155], v198 offset:33792
	ds_read_b128 v[156:159], v198 offset:34816
	ds_read_b128 v[160:163], v198 offset:35840
	ds_read_b128 v[180:183], v198 offset:36864
	ds_read_b128 v[184:187], v198 offset:37888
	ds_read_b128 v[188:191], v198 offset:38912
	ds_read_b128 v[192:195], v198 offset:39936
	global_load_lds_dwordx4 v[200:201], off
	v_lshl_add_u64 v[200:201], s[2:3], 0, v[172:173]
	s_mov_b32 m0, s30
	s_nop 0
	global_load_lds_dwordx4 v[200:201], off
	s_waitcnt lgkmcnt(8)
	s_barrier
	s_waitcnt lgkmcnt(0)
	s_waitcnt lgkmcnt(0)
	v_mfma_f32_16x16x32_bf16 v[128:131], v[132:135], v[148:151], v[128:131]
	v_mfma_f32_16x16x32_bf16 v[124:127], v[140:143], v[148:151], v[124:127]
	v_mfma_f32_16x16x32_bf16 v[120:123], v[132:135], v[156:159], v[120:123]
	v_mfma_f32_16x16x32_bf16 v[116:119], v[140:143], v[156:159], v[116:119]
	v_mfma_f32_16x16x32_bf16 v[112:115], v[132:135], v[180:183], v[112:115]
	v_mfma_f32_16x16x32_bf16 v[108:111], v[140:143], v[180:183], v[108:111]
	v_mfma_f32_16x16x32_bf16 v[104:107], v[132:135], v[188:191], v[104:107]
	v_mfma_f32_16x16x32_bf16 v[100:103], v[140:143], v[188:191], v[100:103]
	v_mfma_f32_16x16x32_bf16 v[128:131], v[136:139], v[152:155], v[128:131]
	v_mfma_f32_16x16x32_bf16 v[124:127], v[144:147], v[152:155], v[124:127]
	v_mfma_f32_16x16x32_bf16 v[120:123], v[136:139], v[160:163], v[120:123]
	v_mfma_f32_16x16x32_bf16 v[116:119], v[144:147], v[160:163], v[116:119]
	v_mfma_f32_16x16x32_bf16 v[112:115], v[136:139], v[184:187], v[112:115]
	v_mfma_f32_16x16x32_bf16 v[108:111], v[144:147], v[184:187], v[108:111]
	v_mfma_f32_16x16x32_bf16 v[104:107], v[136:139], v[192:195], v[104:107]
	v_mfma_f32_16x16x32_bf16 v[100:103], v[144:147], v[192:195], v[100:103]
	s_barrier
	s_add_i32 s16, 0, 0x1c000
	s_add_i32 s2, s52, s22
	v_add_u32_e32 v199, s16, v196
	v_lshl_add_u64 v[168:169], v[168:169], 0, s[28:29]
	s_mov_b32 m0, s2
	ds_read_b128 v[200:203], v199
	ds_read_b128 v[204:207], v199 offset:1024
	ds_read_b128 v[208:211], v199 offset:2048
	ds_read_b128 v[220:223], v199 offset:3072
	global_load_lds_dwordx4 v[168:169], off
	v_lshl_add_u64 v[168:169], v[214:215], 0, s[28:29]
	s_add_i32 m0, s2, 0x2000
	s_nop 0
	global_load_lds_dwordx4 v[168:169], off
	s_barrier
	s_waitcnt lgkmcnt(0)
	s_waitcnt lgkmcnt(0)
	v_mfma_f32_16x16x32_bf16 v[96:99], v[200:203], v[148:151], v[96:99]
	v_mfma_f32_16x16x32_bf16 v[92:95], v[208:211], v[148:151], v[92:95]
	v_mfma_f32_16x16x32_bf16 v[88:91], v[200:203], v[156:159], v[88:91]
	v_mfma_f32_16x16x32_bf16 v[84:87], v[208:211], v[156:159], v[84:87]
	v_mfma_f32_16x16x32_bf16 v[80:83], v[200:203], v[180:183], v[80:83]
	v_mfma_f32_16x16x32_bf16 v[76:79], v[208:211], v[180:183], v[76:79]
	v_mfma_f32_16x16x32_bf16 v[72:75], v[200:203], v[188:191], v[72:75]
	v_mfma_f32_16x16x32_bf16 v[68:71], v[208:211], v[188:191], v[68:71]
	v_mfma_f32_16x16x32_bf16 v[96:99], v[204:207], v[152:155], v[96:99]
	v_mfma_f32_16x16x32_bf16 v[92:95], v[220:223], v[152:155], v[92:95]
	v_mfma_f32_16x16x32_bf16 v[88:91], v[204:207], v[160:163], v[88:91]
	v_mfma_f32_16x16x32_bf16 v[84:87], v[220:223], v[160:163], v[84:87]
	v_mfma_f32_16x16x32_bf16 v[80:83], v[204:207], v[184:187], v[80:83]
	v_mfma_f32_16x16x32_bf16 v[76:79], v[220:223], v[184:187], v[76:79]
	v_mfma_f32_16x16x32_bf16 v[72:75], v[204:207], v[192:195], v[72:75]
	v_mfma_f32_16x16x32_bf16 v[68:71], v[220:223], v[192:195], v[68:71]
	s_mov_b32 m0, s31
	v_lshl_add_u64 v[168:169], v[224:225], 0, s[28:29]
	s_barrier
	ds_read_b128 v[148:151], v198 offset:49152
	ds_read_b128 v[152:155], v198 offset:50176
	ds_read_b128 v[156:159], v198 offset:51200
	ds_read_b128 v[160:163], v198 offset:52224
	ds_read_b128 v[180:183], v198 offset:53248
	ds_read_b128 v[184:187], v198 offset:54272
	ds_read_b128 v[188:191], v198 offset:55296
	ds_read_b128 v[192:195], v198 offset:56320
	global_load_lds_dwordx4 v[168:169], off
	v_lshl_add_u64 v[168:169], v[234:235], 0, s[28:29]
	s_mov_b32 m0, s42
	s_nop 0
	global_load_lds_dwordx4 v[168:169], off
	s_barrier
	s_waitcnt lgkmcnt(0)
	s_waitcnt lgkmcnt(0)
	v_mfma_f32_16x16x32_bf16 v[64:67], v[132:135], v[148:151], v[64:67]
	v_mfma_f32_16x16x32_bf16 v[60:63], v[140:143], v[148:151], v[60:63]
	v_mfma_f32_16x16x32_bf16 v[56:59], v[132:135], v[156:159], v[56:59]
	v_mfma_f32_16x16x32_bf16 v[52:55], v[140:143], v[156:159], v[52:55]
	v_mfma_f32_16x16x32_bf16 v[48:51], v[132:135], v[180:183], v[48:51]
	v_mfma_f32_16x16x32_bf16 v[44:47], v[140:143], v[180:183], v[44:47]
	v_mfma_f32_16x16x32_bf16 v[40:43], v[132:135], v[188:191], v[40:43]
	v_mfma_f32_16x16x32_bf16 v[36:39], v[140:143], v[188:191], v[36:39]
	v_mfma_f32_16x16x32_bf16 v[64:67], v[136:139], v[152:155], v[64:67]
	v_mfma_f32_16x16x32_bf16 v[60:63], v[144:147], v[152:155], v[60:63]
	v_mfma_f32_16x16x32_bf16 v[56:59], v[136:139], v[160:163], v[56:59]
	v_mfma_f32_16x16x32_bf16 v[52:55], v[144:147], v[160:163], v[52:55]
	v_mfma_f32_16x16x32_bf16 v[48:51], v[136:139], v[184:187], v[48:51]
	v_mfma_f32_16x16x32_bf16 v[44:47], v[144:147], v[184:187], v[44:47]
	v_mfma_f32_16x16x32_bf16 v[40:43], v[136:139], v[192:195], v[40:43]
	v_mfma_f32_16x16x32_bf16 v[36:39], v[144:147], v[192:195], v[36:39]
	s_barrier
	s_add_u32 s2, s20, 0x60080
	s_addc_u32 s3, s21, 0
	s_add_i32 s16, s16, s22
	v_lshl_add_u64 v[132:133], s[2:3], 0, v[2:3]
	s_mov_b32 m0, s16
	s_nop 0
	global_load_lds_dwordx4 v[132:133], off
	v_lshl_add_u64 v[132:133], s[2:3], 0, v[174:175]
	s_add_i32 m0, s16, 0x2000
	s_nop 0
	global_load_lds_dwordx4 v[132:133], off
	s_waitcnt vmcnt(6)
	s_barrier
	v_mfma_f32_16x16x32_bf16 v[32:35], v[200:203], v[148:151], v[32:35]
	v_mfma_f32_16x16x32_bf16 v[28:31], v[208:211], v[148:151], v[28:31]
	v_mfma_f32_16x16x32_bf16 v[24:27], v[200:203], v[156:159], v[24:27]
	v_mfma_f32_16x16x32_bf16 v[20:23], v[208:211], v[156:159], v[20:23]
	v_mfma_f32_16x16x32_bf16 v[16:19], v[200:203], v[180:183], v[16:19]
	v_mfma_f32_16x16x32_bf16 v[12:15], v[208:211], v[180:183], v[12:15]
	v_mfma_f32_16x16x32_bf16 v[8:11], v[200:203], v[188:191], v[8:11]
	v_mfma_f32_16x16x32_bf16 v[4:7], v[208:211], v[188:191], v[4:7]
	v_mfma_f32_16x16x32_bf16 v[32:35], v[204:207], v[152:155], v[32:35]
	v_mfma_f32_16x16x32_bf16 v[28:31], v[220:223], v[152:155], v[28:31]
	v_mfma_f32_16x16x32_bf16 v[24:27], v[204:207], v[160:163], v[24:27]
	v_mfma_f32_16x16x32_bf16 v[20:23], v[220:223], v[160:163], v[20:23]
	v_mfma_f32_16x16x32_bf16 v[16:19], v[204:207], v[184:187], v[16:19]
	v_mfma_f32_16x16x32_bf16 v[12:15], v[220:223], v[184:187], v[12:15]
	v_mfma_f32_16x16x32_bf16 v[8:11], v[204:207], v[192:195], v[8:11]
	v_mfma_f32_16x16x32_bf16 v[4:7], v[220:223], v[192:195], v[4:7]
	s_add_u32 s49, s49, 0x100
	s_addc_u32 s50, s50, 0
	s_cmp_ge_i32 s51, s40
	s_mov_b64 s[2:3], s[4:5]
	s_mov_b32 s16, s51
	s_barrier
	s_cbranch_scc0 .LBB0_632
	v_lshl_add_u32 v182, s41, 8, v170
	v_ashrrev_i32_e32 v183, 31, v182
	v_lshl_or_b32 v186, s37, 8, v197
	v_lshlrev_b64 v[184:185], 10, v[182:183]
	v_ashrrev_i32_e32 v187, 31, v186
	v_lshl_add_u64 v[180:181], v[184:185], 0, v[186:187]
	v_readlane_b32 s2, v252, 60
	v_lshlrev_b64 v[134:135], 1, v[180:181]
	v_readlane_b32 s3, v252, 61
	s_cmp_lg_u32 s36, 0
	s_nop 0
	v_lshl_add_u64 v[132:133], s[2:3], 0, v[134:135]
	global_load_dwordx4 v[160:163], v[132:133], off
	s_cselect_b64 s[2:3], -1, 0
	s_and_b64 vcc, exec, s[2:3]
	s_cbranch_vccz .LBB0_635
	s_mov_b64 s[4:5], 0
	s_branch .LBB0_636

.LBB0_638:
	v_add_co_u32_e32 v134, vcc, 0x8000, v132
	s_nop 1
	v_addc_co_u32_e32 v135, vcc, 0, v133, vcc
	global_load_dwordx4 v[156:159], v[134:135], off
	v_cndmask_b32_e64 v134, 0, 1, s[2:3]
	v_cmp_ne_u32_e64 s[40:41], 1, v134
	s_andn2_b64 vcc, exec, s[2:3]
	s_cbranch_vccnz .LBB0_734
	s_cbranch_execnz .LBB0_641

.LBB0_641:
	v_add_co_u32_e32 v134, vcc, 0x10000, v132
	s_nop 1
	v_addc_co_u32_e32 v135, vcc, 0, v133, vcc
	global_load_dwordx4 v[148:151], v[134:135], off
	s_and_b64 vcc, exec, s[40:41]
	s_cbranch_vccnz .LBB0_735
	s_cbranch_execnz .LBB0_644

.LBB0_644:
	v_add_co_u32_e32 v132, vcc, 0x18000, v132
	s_nop 1
	v_addc_co_u32_e32 v133, vcc, 0, v133, vcc
	global_load_dwordx4 v[140:143], v[132:133], off
	s_and_b64 vcc, exec, s[40:41]
	s_cbranch_vccnz .LBB0_736
	s_cbranch_execnz .LBB0_647

.LBB0_659:
	v_add_u32_e32 v132, 0x80, v182
	v_ashrrev_i32_e32 v133, 31, v132
	v_lshlrev_b64 v[188:189], 10, v[132:133]
	v_lshl_add_u64 v[182:183], v[188:189], 0, v[186:187]
	v_readlane_b32 s2, v252, 60
	v_lshlrev_b64 v[134:135], 1, v[182:183]
	v_readlane_b32 s3, v252, 61
	s_and_b64 vcc, exec, s[40:41]
	s_nop 0
	v_lshl_add_u64 v[132:133], s[2:3], 0, v[134:135]
	global_load_dwordx4 v[160:163], v[132:133], off
	s_cbranch_vccnz .LBB0_741
	v_lshl_add_u64 v[190:191], s[16:17], 0, v[134:135]
	s_cbranch_execnz .LBB0_662

.LBB0_662:
	v_add_co_u32_e32 v134, vcc, 0x8000, v132
	s_nop 1
	v_addc_co_u32_e32 v135, vcc, 0, v133, vcc
	global_load_dwordx4 v[156:159], v[134:135], off
	s_and_b64 vcc, exec, s[40:41]
	s_cbranch_vccnz .LBB0_742
	s_cbranch_execnz .LBB0_665

.LBB0_683:
	v_or_b32_e32 v186, 0x80, v186
	v_ashrrev_i32_e32 v187, 31, v186
	v_lshl_add_u64 v[132:133], v[184:185], 0, v[186:187]
	v_readlane_b32 s2, v252, 60
	v_lshlrev_b64 v[134:135], 1, v[132:133]
	v_readlane_b32 s3, v252, 61
	s_and_b64 vcc, exec, s[40:41]
	s_nop 0
	v_lshl_add_u64 v[132:133], s[2:3], 0, v[134:135]
	global_load_dwordx4 v[160:163], v[132:133], off
	s_cbranch_vccnz .LBB0_749
	v_lshl_add_u64 v[184:185], s[16:17], 0, v[134:135]
	s_cbranch_execnz .LBB0_686

.LBB0_707:
	v_lshl_add_u64 v[132:133], v[188:189], 0, v[186:187]
	v_readlane_b32 s2, v252, 60
	v_lshlrev_b64 v[134:135], 1, v[132:133]
	v_readlane_b32 s3, v252, 61
	s_and_b64 vcc, exec, s[40:41]
	s_nop 0
	v_lshl_add_u64 v[132:133], s[2:3], 0, v[134:135]
	global_load_dwordx4 v[160:163], v[132:133], off
	s_cbranch_vccnz .LBB0_757
	v_lshl_add_u64 v[180:181], s[16:17], 0, v[134:135]
	s_cbranch_execnz .LBB0_710
